# hgrn local: the 16 per-token forget-gate LDS reads of the first chunk issued together (were one per token behind a full wait)
# baseline (speedup 1.0000x reference)
; #define LAS __attribute__((address_space(3)))
; __device__ __forceinline__ float bf1(bf16 h) { return __uint_as_float(((unsigned)h) << 16); }
; __device__ __forceinline__ float sigmf(float v) { return __builtin_amdgcn_rcpf(1.0f + __builtin_amdgcn_exp2f(-1.4426950408889634f * v)); }
; template <bool OUT> __device__ __forceinline__ void hgrn_chunk(const PA& a, LAS unsigned char* wb, LAS float* DLk, LAS float* E7k, LAS float* DALLk, int layer, int h, int lane, const HRaw& raw, ...
;     ...
;         {
;             u16 vr[16];
; #pragma unroll
;             for (int t = 0; t < 16; ++t) vr[t] = RV[t * 72 + lane];
;             const v4u w0 = {(unsigned)vr[0] | ((unsigned)vr[1] << 16), (unsigned)vr[2] | ((unsigned)vr[3] << 16), (unsigned)vr[4] | ((unsigned)vr[5] << 16), (unsigned)vr[6] | ((unsigned)vr[7] << 16)};
;             const v4u w1 = {(unsigned)vr[8] | ((unsigned)vr[9] << 16), (unsigned)vr[10] | ((unsigned)vr[11] << 16), (unsigned)vr[12] | ((unsigned)vr[13] << 16), (unsigned)vr[14] | ((unsigned)vr[15] << 16)};
;             *(LAS v4u*)(VT + lane * 24) = w0; *(LAS v4u*)(VT + lane * 24 + 8) = w1;
;         }
;         float cum[16], kk[16]; float run = 0.f;
; #pragma unroll
;         for (int t = 0; t < 16; ++t) { const float sg = sigmf(bf1(RF[t * 72 + lane])); const float f = lb + (1.f - lb) * sg; kk[t] = (1.f - lb) * (1.f - sg); run += fmaxf(__logf(f), -69.f); cum[t] = run; }
.LBB0_462:
	s_nop 0
	v_mov_b32_e32 v177, v1
	ds_read_u16 v2, v146 offset:2304
	ds_read_u16 v6, v146 offset:2448
	ds_read_u16 v3, v146 offset:2592
	ds_read_u16 v7, v146 offset:2736
	ds_read_u16 v4, v146 offset:2880
	ds_read_u16 v8, v146 offset:3024
	ds_read_u16 v5, v146 offset:3168
	ds_read_u16 v9, v146 offset:3312
	ds_read_u16 v10, v146 offset:3456
	ds_read_u16 v11, v146 offset:3600
	ds_read_u16 v12, v146 offset:3744
	ds_read_u16 v13, v146 offset:3888
	ds_read_u16 v14, v146 offset:4032
	ds_read_u16 v15, v146 offset:4176
	ds_read_u16 v16, v146 offset:4320
	ds_read_u16 v17, v146 offset:4464
	s_mov_b32 s2, 0x5040100
	s_waitcnt lgkmcnt(8)
	v_perm_b32 v5, v9, v5, s2
	v_perm_b32 v4, v8, v4, s2
	v_perm_b32 v3, v7, v3, s2
	v_perm_b32 v2, v6, v2, s2
	s_waitcnt lgkmcnt(0)
	v_perm_b32 v9, v17, v16, s2
	v_perm_b32 v8, v15, v14, s2
	v_perm_b32 v7, v13, v12, s2
	v_perm_b32 v6, v11, v10, s2
	ds_write_b128 v147, v[2:5] offset:7680
	ds_write_b128 v147, v[6:9] offset:7696
	ds_read_u16 v3, v148
	ds_read_u16 v184, v148 offset:144
	ds_read_u16 v185, v148 offset:288
	ds_read_u16 v186, v148 offset:432
	ds_read_u16 v187, v148 offset:576
	ds_read_u16 v188, v148 offset:720
	ds_read_u16 v189, v148 offset:864
	ds_read_u16 v190, v148 offset:1008
	ds_read_u16 v191, v148 offset:1152
	ds_read_u16 v192, v148 offset:1296
	ds_read_u16 v193, v148 offset:1440
	ds_read_u16 v194, v148 offset:1584
	ds_read_u16 v195, v148 offset:1728
	ds_read_u16 v196, v148 offset:1872
	ds_read_u16 v197, v148 offset:2016
	ds_read_u16 v198, v148 offset:2160
	v_sub_f32_e32 v2, 1.0, v1
	s_waitcnt lgkmcnt(0)
	v_lshlrev_b32_e32 v3, 16, v3
	v_mul_f32_e32 v3, 0xbfb8aa3b, v3
	v_exp_f32_e32 v3, v3
	s_nop 0
	v_add_f32_e32 v3, 1.0, v3
	v_rcp_f32_e32 v4, v3
	s_nop 0
	v_fma_f32 v3, v2, v4, v1
	v_cmp_gt_f32_e32 vcc, s27, v3
	s_nop 1
	v_cndmask_b32_e64 v5, 0, 32, vcc
	v_ldexp_f32 v3, v3, v5
	v_log_f32_e32 v3, v3
	s_nop 0
	v_mul_f32_e32 v5, 0x3f317217, v3
	v_fma_f32 v5, v3, s80, -v5
	v_fmac_f32_e32 v5, 0x3377d1cf, v3
	v_fmac_f32_e32 v5, 0x3f317217, v3
	v_cmp_lt_f32_e64 s[42:43], |v3|, s81
	s_nop 1
	v_cndmask_b32_e64 v3, v3, v5, s[42:43]
	v_cndmask_b32_e32 v5, 0, v238, vcc
	v_sub_f32_e32 v3, v3, v5
	v_max_f32_e32 v3, 0xc28a0000, v3
	v_add_f32_e32 v3, 0, v3
	s_waitcnt lgkmcnt(0)
	v_lshlrev_b32_e32 v5, 16, v184
	v_mul_f32_e32 v5, 0xbfb8aa3b, v5
	v_exp_f32_e32 v5, v5
	s_nop 0
	v_add_f32_e32 v5, 1.0, v5
	v_rcp_f32_e32 v6, v5
	s_nop 0
	v_fma_f32 v5, v2, v6, v1
	v_cmp_gt_f32_e32 vcc, s27, v5
	s_nop 1
	v_cndmask_b32_e64 v7, 0, 32, vcc
	v_ldexp_f32 v5, v5, v7
	v_log_f32_e32 v5, v5
	s_nop 0
	v_mul_f32_e32 v7, 0x3f317217, v5
	v_fma_f32 v7, v5, s80, -v7
	v_fmac_f32_e32 v7, 0x3377d1cf, v5
	v_fmac_f32_e32 v7, 0x3f317217, v5
	v_cmp_lt_f32_e64 s[42:43], |v5|, s81
	s_nop 1
	v_cndmask_b32_e64 v5, v5, v7, s[42:43]
	v_cndmask_b32_e32 v7, 0, v238, vcc
	v_sub_f32_e32 v5, v5, v7
	v_max_f32_e32 v5, 0xc28a0000, v5
	v_add_f32_e32 v20, v3, v5
	s_waitcnt lgkmcnt(0)
	v_lshlrev_b32_e32 v5, 16, v185
	v_mul_f32_e32 v5, 0xbfb8aa3b, v5
	v_exp_f32_e32 v5, v5
	s_nop 0
	v_add_f32_e32 v5, 1.0, v5
	v_rcp_f32_e32 v5, v5
	s_nop 0
	v_fma_f32 v7, v2, v5, v1
	v_cmp_gt_f32_e32 vcc, s27, v7
	v_pk_add_f32 v[4:5], v[4:5], 1.0 op_sel_hi:[1,0] neg_lo:[1,0] neg_hi:[1,0]
	s_nop 0
	v_cndmask_b32_e64 v8, 0, 32, vcc
	v_ldexp_f32 v7, v7, v8
	v_log_f32_e32 v7, v7
	s_nop 0
	v_mul_f32_e32 v8, 0x3f317217, v7
	v_fma_f32 v8, v7, s80, -v8
	v_fmac_f32_e32 v8, 0x3377d1cf, v7
	v_fmac_f32_e32 v8, 0x3f317217, v7
	v_cmp_lt_f32_e64 s[42:43], |v7|, s81
	s_nop 1
	v_cndmask_b32_e64 v7, v7, v8, s[42:43]
	v_cndmask_b32_e32 v8, 0, v238, vcc
	v_sub_f32_e32 v7, v7, v8
	v_max_f32_e32 v7, 0xc28a0000, v7
	v_add_f32_e32 v21, v20, v7
	s_waitcnt lgkmcnt(0)
	v_lshlrev_b32_e32 v7, 16, v186
	v_mul_f32_e32 v7, 0xbfb8aa3b, v7
	v_exp_f32_e32 v7, v7
	s_nop 0
	v_add_f32_e32 v7, 1.0, v7
	v_rcp_f32_e32 v7, v7
	s_nop 0
	v_fma_f32 v8, v2, v7, v1
	v_cmp_gt_f32_e32 vcc, s27, v8
	v_pk_add_f32 v[6:7], v[6:7], 1.0 op_sel_hi:[1,0] neg_lo:[1,0] neg_hi:[1,0]
	s_nop 0
	v_cndmask_b32_e64 v9, 0, 32, vcc
	v_ldexp_f32 v8, v8, v9
	v_log_f32_e32 v8, v8
	s_nop 0
	v_mul_f32_e32 v9, 0x3f317217, v8
	v_fma_f32 v9, v8, s80, -v9
	v_fmac_f32_e32 v9, 0x3377d1cf, v8
	v_fmac_f32_e32 v9, 0x3f317217, v8
	v_cmp_lt_f32_e64 s[42:43], |v8|, s81
	s_nop 1
	v_cndmask_b32_e64 v8, v8, v9, s[42:43]
	v_cndmask_b32_e32 v9, 0, v238, vcc
	v_sub_f32_e32 v8, v8, v9
	v_max_f32_e32 v8, 0xc28a0000, v8
	v_add_f32_e32 v22, v21, v8
	s_waitcnt lgkmcnt(0)
	v_lshlrev_b32_e32 v8, 16, v187
	v_mul_f32_e32 v8, 0xbfb8aa3b, v8
	v_exp_f32_e32 v8, v8
	s_nop 0
	v_add_f32_e32 v8, 1.0, v8
	v_rcp_f32_e32 v8, v8
	s_nop 0
	v_fma_f32 v9, v2, v8, v1
	v_cmp_gt_f32_e32 vcc, s27, v9
	s_nop 1
	v_cndmask_b32_e64 v10, 0, 32, vcc
	v_ldexp_f32 v9, v9, v10
	v_log_f32_e32 v9, v9
	s_nop 0
	v_mul_f32_e32 v10, 0x3f317217, v9
	v_fma_f32 v10, v9, s80, -v10
	v_fmac_f32_e32 v10, 0x3377d1cf, v9
	v_fmac_f32_e32 v10, 0x3f317217, v9
	v_cmp_lt_f32_e64 s[42:43], |v9|, s81
	s_nop 1
	v_cndmask_b32_e64 v9, v9, v10, s[42:43]
	v_cndmask_b32_e32 v10, 0, v238, vcc
	v_sub_f32_e32 v9, v9, v10
	v_max_f32_e32 v9, 0xc28a0000, v9
	v_add_f32_e32 v23, v22, v9
	s_waitcnt lgkmcnt(0)
	v_lshlrev_b32_e32 v9, 16, v188
	v_mul_f32_e32 v9, 0xbfb8aa3b, v9
	v_exp_f32_e32 v9, v9
	s_nop 0
	v_add_f32_e32 v9, 1.0, v9
	v_rcp_f32_e32 v10, v9
	s_nop 0
	v_fma_f32 v9, v2, v10, v1
	v_cmp_gt_f32_e32 vcc, s27, v9
	s_nop 1
	v_cndmask_b32_e64 v11, 0, 32, vcc
	v_ldexp_f32 v9, v9, v11
	v_log_f32_e32 v9, v9
	s_nop 0
	v_mul_f32_e32 v11, 0x3f317217, v9
	v_fma_f32 v11, v9, s80, -v11
	v_fmac_f32_e32 v11, 0x3377d1cf, v9
	v_fmac_f32_e32 v11, 0x3f317217, v9
	v_cmp_lt_f32_e64 s[42:43], |v9|, s81
	s_nop 1
	v_cndmask_b32_e64 v9, v9, v11, s[42:43]
	v_cndmask_b32_e32 v11, 0, v238, vcc
	v_sub_f32_e32 v9, v9, v11
	v_max_f32_e32 v9, 0xc28a0000, v9
	v_add_f32_e32 v24, v23, v9
	s_waitcnt lgkmcnt(0)
; __device__ __forceinline__ float bf1(bf16 h) { return __uint_as_float(((unsigned)h) << 16); }
; __device__ __forceinline__ float sigmf(float v) { return __builtin_amdgcn_rcpf(1.0f + __builtin_amdgcn_exp2f(-1.4426950408889634f * v)); }
; template <bool OUT> __device__ __forceinline__ void hgrn_chunk(const PA& a, LAS unsigned char* wb, LAS float* DLk, LAS float* E7k, LAS float* DALLk, int layer, int h, int lane, const HRaw& raw, ...
;     ...
;         for (int t = 0; t < 16; ++t) { const float sg = sigmf(bf1(RF[t * 72 + lane])); const float f = lb + (1.f - lb) * sg; kk[t] = (1.f - lb) * (1.f - sg); run += fmaxf(__logf(f), -69.f); cum[t] = run; }
	v_lshlrev_b32_e32 v9, 16, v189
	v_mul_f32_e32 v9, 0xbfb8aa3b, v9
	v_exp_f32_e32 v9, v9
	s_nop 0
	v_add_f32_e32 v9, 1.0, v9
	v_rcp_f32_e32 v9, v9
	s_nop 0
	v_fma_f32 v11, v2, v9, v1
	v_cmp_gt_f32_e32 vcc, s27, v11
	v_pk_add_f32 v[8:9], v[8:9], 1.0 op_sel_hi:[1,0] neg_lo:[1,0] neg_hi:[1,0]
	s_nop 0
	v_cndmask_b32_e64 v12, 0, 32, vcc
	v_ldexp_f32 v11, v11, v12
	v_log_f32_e32 v11, v11
	s_nop 0
	v_mul_f32_e32 v12, 0x3f317217, v11
	v_fma_f32 v12, v11, s80, -v12
	v_fmac_f32_e32 v12, 0x3377d1cf, v11
	v_fmac_f32_e32 v12, 0x3f317217, v11
	v_cmp_lt_f32_e64 s[42:43], |v11|, s81
	s_nop 1
	v_cndmask_b32_e64 v11, v11, v12, s[42:43]
	v_cndmask_b32_e32 v12, 0, v238, vcc
	v_sub_f32_e32 v11, v11, v12
	v_max_f32_e32 v11, 0xc28a0000, v11
	v_add_f32_e32 v25, v24, v11
	s_waitcnt lgkmcnt(0)
	v_lshlrev_b32_e32 v11, 16, v190
	v_mul_f32_e32 v11, 0xbfb8aa3b, v11
	v_exp_f32_e32 v11, v11
	s_nop 0
	v_add_f32_e32 v11, 1.0, v11
	v_rcp_f32_e32 v11, v11
	s_nop 0
	v_fma_f32 v12, v2, v11, v1
	v_cmp_gt_f32_e32 vcc, s27, v12
	v_pk_add_f32 v[10:11], v[10:11], 1.0 op_sel_hi:[1,0] neg_lo:[1,0] neg_hi:[1,0]
	s_nop 0
	v_cndmask_b32_e64 v13, 0, 32, vcc
	v_ldexp_f32 v12, v12, v13
	v_log_f32_e32 v12, v12
	s_nop 0
	v_mul_f32_e32 v13, 0x3f317217, v12
	v_fma_f32 v13, v12, s80, -v13
	v_fmac_f32_e32 v13, 0x3377d1cf, v12
	v_fmac_f32_e32 v13, 0x3f317217, v12
	v_cmp_lt_f32_e64 s[42:43], |v12|, s81
	s_nop 1
	v_cndmask_b32_e64 v12, v12, v13, s[42:43]
	v_cndmask_b32_e32 v13, 0, v238, vcc
	v_sub_f32_e32 v12, v12, v13
	v_max_f32_e32 v12, 0xc28a0000, v12
	v_add_f32_e32 v26, v25, v12
	s_waitcnt lgkmcnt(0)
	v_lshlrev_b32_e32 v12, 16, v191
	v_mul_f32_e32 v12, 0xbfb8aa3b, v12
	v_exp_f32_e32 v12, v12
	s_nop 0
	v_add_f32_e32 v12, 1.0, v12
	v_rcp_f32_e32 v12, v12
	s_nop 0
	v_fma_f32 v13, v2, v12, v1
	v_cmp_gt_f32_e32 vcc, s27, v13
	s_nop 1
	v_cndmask_b32_e64 v14, 0, 32, vcc
	v_ldexp_f32 v13, v13, v14
	v_log_f32_e32 v13, v13
	s_nop 0
	v_mul_f32_e32 v14, 0x3f317217, v13
	v_fma_f32 v14, v13, s80, -v14
	v_fmac_f32_e32 v14, 0x3377d1cf, v13
	v_fmac_f32_e32 v14, 0x3f317217, v13
	v_cmp_lt_f32_e64 s[42:43], |v13|, s81
	s_nop 1
	v_cndmask_b32_e64 v13, v13, v14, s[42:43]
	v_cndmask_b32_e32 v14, 0, v238, vcc
	v_sub_f32_e32 v13, v13, v14
	v_max_f32_e32 v13, 0xc28a0000, v13
	v_add_f32_e32 v27, v26, v13
	s_waitcnt lgkmcnt(0)
	v_lshlrev_b32_e32 v13, 16, v192
	v_mul_f32_e32 v13, 0xbfb8aa3b, v13
	v_exp_f32_e32 v13, v13
	s_nop 0
	v_add_f32_e32 v13, 1.0, v13
	v_rcp_f32_e32 v14, v13
	s_nop 0
	v_fma_f32 v13, v2, v14, v1
	v_cmp_gt_f32_e32 vcc, s27, v13
	s_nop 1
	v_cndmask_b32_e64 v15, 0, 32, vcc
	v_ldexp_f32 v13, v13, v15
	v_log_f32_e32 v13, v13
	s_nop 0
	v_mul_f32_e32 v15, 0x3f317217, v13
	v_fma_f32 v15, v13, s80, -v15
	v_fmac_f32_e32 v15, 0x3377d1cf, v13
	v_fmac_f32_e32 v15, 0x3f317217, v13
	v_cmp_lt_f32_e64 s[42:43], |v13|, s81
	s_nop 1
	v_cndmask_b32_e64 v13, v13, v15, s[42:43]
	v_cndmask_b32_e32 v15, 0, v238, vcc
	v_sub_f32_e32 v13, v13, v15
	v_max_f32_e32 v13, 0xc28a0000, v13
	v_add_f32_e32 v28, v27, v13
	s_waitcnt lgkmcnt(0)
	v_lshlrev_b32_e32 v13, 16, v193
	v_mul_f32_e32 v13, 0xbfb8aa3b, v13
	v_exp_f32_e32 v13, v13
	s_nop 0
	v_add_f32_e32 v13, 1.0, v13
	v_rcp_f32_e32 v13, v13
	s_nop 0
	v_fma_f32 v15, v2, v13, v1
	v_cmp_gt_f32_e32 vcc, s27, v15
	s_nop 1
	v_cndmask_b32_e64 v16, 0, 32, vcc
	v_ldexp_f32 v15, v15, v16
	v_log_f32_e32 v15, v15
	s_nop 0
	v_mul_f32_e32 v16, 0x3f317217, v15
	v_fma_f32 v16, v15, s80, -v16
	v_fmac_f32_e32 v16, 0x3377d1cf, v15
	v_fmac_f32_e32 v16, 0x3f317217, v15
	v_cmp_lt_f32_e64 s[42:43], |v15|, s81
	s_nop 1
	v_cndmask_b32_e64 v15, v15, v16, s[42:43]
	v_cndmask_b32_e32 v16, 0, v238, vcc
	v_sub_f32_e32 v15, v15, v16
	v_max_f32_e32 v15, 0xc28a0000, v15
	v_add_f32_e32 v29, v28, v15
	s_waitcnt lgkmcnt(0)
	v_lshlrev_b32_e32 v15, 16, v194
	v_mul_f32_e32 v15, 0xbfb8aa3b, v15
	v_exp_f32_e32 v15, v15
	s_nop 0
	v_add_f32_e32 v15, 1.0, v15
	v_rcp_f32_e32 v15, v15
	s_nop 0
	v_fma_f32 v16, v2, v15, v1
	v_cmp_gt_f32_e32 vcc, s27, v16
	s_nop 1
	v_cndmask_b32_e64 v17, 0, 32, vcc
	v_ldexp_f32 v16, v16, v17
	v_log_f32_e32 v16, v16
	s_nop 0
	v_mul_f32_e32 v17, 0x3f317217, v16
	v_fma_f32 v17, v16, s80, -v17
	v_fmac_f32_e32 v17, 0x3377d1cf, v16
	v_fmac_f32_e32 v17, 0x3f317217, v16
	v_cmp_lt_f32_e64 s[42:43], |v16|, s81
	s_nop 1
	v_cndmask_b32_e64 v16, v16, v17, s[42:43]
	v_cndmask_b32_e32 v17, 0, v238, vcc
	v_sub_f32_e32 v16, v16, v17
	v_max_f32_e32 v16, 0xc28a0000, v16
	v_add_f32_e32 v30, v29, v16
	s_waitcnt lgkmcnt(0)
	v_lshlrev_b32_e32 v16, 16, v195
	v_mul_f32_e32 v16, 0xbfb8aa3b, v16
	v_exp_f32_e32 v16, v16
	s_nop 0
	v_add_f32_e32 v16, 1.0, v16
	v_rcp_f32_e32 v16, v16
	s_nop 0
	v_fma_f32 v17, v2, v16, v1
	v_cmp_gt_f32_e32 vcc, s27, v17
	s_nop 1
	v_cndmask_b32_e64 v18, 0, 32, vcc
	v_ldexp_f32 v17, v17, v18
	v_log_f32_e32 v17, v17
	s_nop 0
	v_mul_f32_e32 v18, 0x3f317217, v17
	v_fma_f32 v18, v17, s80, -v18
	v_fmac_f32_e32 v18, 0x3377d1cf, v17
	v_fmac_f32_e32 v18, 0x3f317217, v17
	v_cmp_lt_f32_e64 s[42:43], |v17|, s81
	s_nop 1
	v_cndmask_b32_e64 v17, v17, v18, s[42:43]
	v_cndmask_b32_e32 v18, 0, v238, vcc
	v_sub_f32_e32 v17, v17, v18
	v_max_f32_e32 v17, 0xc28a0000, v17
	v_add_f32_e32 v31, v30, v17
	s_waitcnt lgkmcnt(0)
	v_lshlrev_b32_e32 v17, 16, v196
	v_mul_f32_e32 v17, 0xbfb8aa3b, v17
	v_exp_f32_e32 v17, v17
	s_nop 0
	v_add_f32_e32 v17, 1.0, v17
	v_rcp_f32_e32 v18, v17
	s_nop 0
	v_fma_f32 v17, v2, v18, v1
	v_cmp_gt_f32_e32 vcc, s27, v17
	s_nop 1
	v_cndmask_b32_e64 v19, 0, 32, vcc
	v_ldexp_f32 v17, v17, v19
	v_log_f32_e32 v17, v17
	s_nop 0
	v_mul_f32_e32 v19, 0x3f317217, v17
	v_fma_f32 v19, v17, s80, -v19
	v_fmac_f32_e32 v19, 0x3377d1cf, v17
	v_fmac_f32_e32 v19, 0x3f317217, v17
	v_cmp_lt_f32_e64 s[42:43], |v17|, s81
	s_nop 1
	v_cndmask_b32_e64 v17, v17, v19, s[42:43]
	v_cndmask_b32_e32 v19, 0, v238, vcc
	v_sub_f32_e32 v17, v17, v19
	v_max_f32_e32 v17, 0xc28a0000, v17
	v_add_f32_e32 v32, v31, v17
	s_waitcnt lgkmcnt(0)
; #define LAS __attribute__((address_space(3)))
; #define LDS_WAIT() asm volatile("s_waitcnt lgkmcnt(0)" ::: "memory")
; __device__ __forceinline__ unsigned f2bf(float f) { unsigned u = __builtin_bit_cast(unsigned, f); return (u + 0x7fffu + ((u >> 16) & 1u)) >> 16; }
; __device__ __forceinline__ float bf1(bf16 h) { return __uint_as_float(((unsigned)h) << 16); }
; __device__ __forceinline__ float sigmf(float v) { return __builtin_amdgcn_rcpf(1.0f + __builtin_amdgcn_exp2f(-1.4426950408889634f * v)); }
; __device__ __forceinline__ float siluf(float v) { return v * sigmf(v); }
; __device__ __forceinline__ bf16x8 pk8(const float* v) { v4u w = {pk2(v[0], v[1]), pk2(v[2], v[3]), pk2(v[4], v[5]), pk2(v[6], v[7])}; return __builtin_bit_cast(bf16x8, w); }
; template <bool OUT> __device__ __forceinline__ void hgrn_chunk(const PA& a, LAS unsigned char* wb, LAS float* DLk, LAS float* E7k, LAS float* DALLk, int layer, int h, int lane, const HRaw& raw, ...
;     ...
;         for (int t = 0; t < 16; ++t) { const float sg = sigmf(bf1(RF[t * 72 + lane])); const float f = lb + (1.f - lb) * sg; kk[t] = (1.f - lb) * (1.f - sg); run += fmaxf(__logf(f), -69.f); cum[t] = run; }
;         const float cl = cum[15], c7 = cum[7];
;         DLk[lane] = __expf(cl);
;         if (OUT) E7k[lane] = __expf(c7); else DALLk[lane] = cl;
;         if (OUT) {
;             float qv[16];
; #pragma unroll
;             for (int t = 0; t < 16; ++t) qv[t] = bf1(RQ[t * 72 + lane]);
;             LDS_WAIT();
; #pragma unroll
;             for (int t = 0; t < 16; ++t) {
;                 QT[t * 72 + lane] = (bf16)f2bf(siluf(qv[t]) * __expf(fminf(cum[t] - c7, 60.f)));
;                 KT[t * 72 + lane] = (bf16)f2bf(kk[t] * __expf(fminf(c7 - cum[t], 60.f)));
;             }
;         }
;         LDS_WAIT();
;         float kh[16];
; #pragma unroll
;         for (int t = 0; t < 16; ++t) kh[t] = kk[t] * __expf(cl - cum[t]);
;         *(LAS bf16x8*)(KHT + lane * 24) = pk8(kh); *(LAS bf16x8*)(KHT + lane * 24 + 8) = pk8(kh + 8);
	v_lshlrev_b32_e32 v17, 16, v197
	v_mul_f32_e32 v17, 0xbfb8aa3b, v17
	v_exp_f32_e32 v17, v17
	s_nop 0
	v_add_f32_e32 v17, 1.0, v17
	v_rcp_f32_e32 v17, v17
	s_nop 0
	v_fma_f32 v19, v2, v17, v1
	v_cmp_gt_f32_e32 vcc, s27, v19
	s_nop 1
	v_cndmask_b32_e64 v33, 0, 32, vcc
	v_ldexp_f32 v19, v19, v33
	v_log_f32_e32 v19, v19
	s_nop 0
	v_mul_f32_e32 v33, 0x3f317217, v19
	v_fma_f32 v33, v19, s80, -v33
	v_fmac_f32_e32 v33, 0x3377d1cf, v19
	v_fmac_f32_e32 v33, 0x3f317217, v19
	v_cmp_lt_f32_e64 s[42:43], |v19|, s81
	s_nop 1
	v_cndmask_b32_e64 v19, v19, v33, s[42:43]
	v_cndmask_b32_e32 v33, 0, v238, vcc
	v_sub_f32_e32 v19, v19, v33
	v_max_f32_e32 v19, 0xc28a0000, v19
	v_add_f32_e32 v33, v32, v19
	s_waitcnt lgkmcnt(0)
	v_lshlrev_b32_e32 v19, 16, v198
	v_mul_f32_e32 v19, 0xbfb8aa3b, v19
	v_exp_f32_e32 v19, v19
	s_nop 0
	v_add_f32_e32 v19, 1.0, v19
	v_rcp_f32_e32 v19, v19
	s_nop 0
	v_fmac_f32_e32 v1, v2, v19
	v_cmp_gt_f32_e32 vcc, s27, v1
	s_nop 1
	v_cndmask_b32_e64 v34, 0, 32, vcc
	v_ldexp_f32 v1, v1, v34
	v_log_f32_e32 v1, v1
	s_nop 0
	v_mul_f32_e32 v34, 0x3f317217, v1
	v_fma_f32 v34, v1, s80, -v34
	v_fmac_f32_e32 v34, 0x3377d1cf, v1
	v_fmac_f32_e32 v34, 0x3f317217, v1
	v_cmp_lt_f32_e64 s[42:43], |v1|, s81
	s_nop 1
	v_cndmask_b32_e64 v1, v1, v34, s[42:43]
	v_cndmask_b32_e32 v34, 0, v238, vcc
	v_sub_f32_e32 v1, v1, v34
	v_max_f32_e32 v1, 0xc28a0000, v1
	v_add_f32_e32 v1, v33, v1
	v_mul_f32_e32 v34, 0x3fb8aa3b, v1
	v_exp_f32_e32 v34, v34
	v_sub_f32_e32 v3, v1, v3
	v_mul_f32_e32 v3, 0x3fb8aa3b, v3
	ds_write_b32 v149, v34 offset:11520
	ds_write_b32 v150, v1
	v_exp_f32_e32 v34, v3
	v_sub_f32_e32 v3, v1, v20
	v_mul_f32_e32 v3, 0x3fb8aa3b, v3
	v_exp_f32_e32 v20, v3
	v_sub_f32_e32 v3, v1, v21
	v_mul_f32_e32 v3, 0x3fb8aa3b, v3
	v_exp_f32_e32 v35, v3
	v_sub_f32_e32 v3, v1, v22
	v_mul_f32_e32 v3, 0x3fb8aa3b, v3
	v_exp_f32_e32 v21, v3
	v_sub_f32_e32 v3, v1, v23
	v_mul_f32_e32 v3, 0x3fb8aa3b, v3
	v_exp_f32_e32 v22, v3
	v_sub_f32_e32 v3, v1, v24
	v_mul_f32_e32 v3, 0x3fb8aa3b, v3
	v_exp_f32_e32 v24, v3
	v_sub_f32_e32 v3, v1, v25
	v_mul_f32_e32 v3, 0x3fb8aa3b, v3
	v_exp_f32_e32 v23, v3
	v_sub_f32_e32 v3, v1, v26
	v_mul_f32_e32 v3, 0x3fb8aa3b, v3
	v_exp_f32_e32 v25, v3
	v_sub_f32_e32 v3, v1, v27
	v_mul_f32_e32 v3, 0x3fb8aa3b, v3
	v_exp_f32_e32 v26, v3
	v_sub_f32_e32 v3, v1, v28
	v_mul_f32_e32 v3, 0x3fb8aa3b, v3
	v_exp_f32_e32 v28, v3
	v_sub_f32_e32 v3, v1, v29
	v_mul_f32_e32 v3, 0x3fb8aa3b, v3
	v_exp_f32_e32 v27, v3
	v_sub_f32_e32 v3, v1, v30
	v_mul_f32_e32 v3, 0x3fb8aa3b, v3
	v_exp_f32_e32 v29, v3
	v_sub_f32_e32 v3, v1, v31
	v_mul_f32_e32 v3, 0x3fb8aa3b, v3
	v_exp_f32_e32 v30, v3
	v_sub_f32_e32 v3, v1, v32
	v_mul_f32_e32 v3, 0x3fb8aa3b, v3
	v_exp_f32_e32 v32, v3
	v_sub_f32_e32 v3, v1, v33
	v_mul_f32_e32 v3, 0x3fb8aa3b, v3
	v_sub_f32_e32 v1, v1, v1
	v_pk_mul_f32 v[6:7], v[2:3], v[6:7] op_sel_hi:[0,1]
	v_pk_mul_f32 v[10:11], v[2:3], v[10:11] op_sel_hi:[0,1]
	v_mul_f32_e32 v1, 0x3fb8aa3b, v1
	v_pk_mul_f32 v[4:5], v[2:3], v[4:5] op_sel_hi:[0,1]
	v_pk_mul_f32 v[6:7], v[6:7], v[20:21]
	v_pk_mul_f32 v[8:9], v[2:3], v[8:9] op_sel_hi:[0,1]
	v_pk_mul_f32 v[10:11], v[10:11], v[24:25]
	v_exp_f32_e32 v31, v3
	v_exp_f32_e32 v33, v1
	v_pk_mul_f32 v[4:5], v[4:5], v[34:35]
	v_pk_mul_f32 v[8:9], v[8:9], v[22:23]
	v_bfe_u32 v1, v11, 16, 1
	v_bfe_u32 v3, v10, 16, 1
	v_bfe_u32 v20, v7, 16, 1
	v_bfe_u32 v21, v6, 16, 1
	v_add3_u32 v21, v6, v21, s73
	v_add3_u32 v20, v7, v20, s73
	v_add3_u32 v3, v10, v3, s73
	v_add3_u32 v1, v11, v1, s73
	v_bfe_u32 v6, v8, 16, 1
	v_bfe_u32 v7, v9, 16, 1
	v_bfe_u32 v10, v4, 16, 1
	v_bfe_u32 v11, v5, 16, 1
	v_add3_u32 v7, v9, v7, s73
	v_add3_u32 v6, v8, v6, s73
	v_add3_u32 v5, v5, v11, s73
	v_add3_u32 v4, v4, v10, s73
	v_lshrrev_b32_e32 v6, 16, v6
	v_lshrrev_b32_e32 v7, 16, v7
	v_lshrrev_b32_e32 v4, 16, v4
	v_lshrrev_b32_e32 v5, 16, v5
	v_and_or_b32 v7, v1, s26, v7
	v_and_or_b32 v6, v3, s26, v6
	v_and_or_b32 v5, v20, s26, v5
	v_and_or_b32 v4, v21, s26, v4
	s_waitcnt lgkmcnt(0)
; #define LAS __attribute__((address_space(3)))
; #define LDS_WAIT() asm volatile("s_waitcnt lgkmcnt(0)" ::: "memory")
; __device__ __forceinline__ bf16x8 pk8(const float* v) { v4u w = {pk2(v[0], v[1]), pk2(v[2], v[3]), pk2(v[4], v[5]), pk2(v[6], v[7])}; return __builtin_bit_cast(bf16x8, w); }
; template <bool OUT> __device__ __forceinline__ void hgrn_chunk(const PA& a, LAS unsigned char* wb, LAS float* DLk, LAS float* E7k, LAS float* DALLk, int layer, int h, int lane, const HRaw& raw, ...
;     ...
;         for (int k = 0; k < 2; ++k) { *(LAS v4u*)(RF + (rr + 8 * k) * 72 + cc) = raw.f[k]; *(LAS v4u*)(RV + (rr + 8 * k) * 72 + cc) = raw.v[k]; if (OUT) *(LAS v4u*)(RQ + (rr + 8 * k) * 72 + cc) = raw.q[k]; }
;     ...
;         for (int t = 0; t < 16; ++t) kh[t] = kk[t] * __expf(cl - cum[t]);
;         *(LAS bf16x8*)(KHT + lane * 24) = pk8(kh); *(LAS bf16x8*)(KHT + lane * 24 + 8) = pk8(kh + 8);
;     }
;     LDS_WAIT();
;     bf16x8 vfr[4];
; #pragma unroll
;     for (int nt = 0; nt < 4; ++nt) vfr[nt] = (q < 2) ? *(const LAS bf16x8*)(VT + (16 * nt + l15) * 24 + q * 8) : zero8;
; #pragma unroll
;     for (int mt = 0; mt < 4; ++mt) { const bf16x8 afr = (q < 2) ? *(const LAS bf16x8*)(KHT + (16 * mt + l15) * 24 + q * 8) : zero8;
; #pragma unroll
;         for (int nt = 0; nt < 4; ++nt) U[mt][nt] = __builtin_amdgcn_mfma_f32_16x16x32_bf16(afr, vfr[nt], (f32x4){0.f, 0.f, 0.f, 0.f}, 0, 0, 0); }
; template <bool OUT> __device__ __forceinline__ void hgrn_pair(const PA& a, LAS unsigned char* lds, int layer, int bh, int s, int wave, int lane) {
;     ...
;     { const HRaw r1 = hgrn_loadc<OUT>(a, bh, c, 2 * wl + 1, lane); hgrn_chunk<OUT>(a, wb, DLs + 64, DLs + 192, DALL + (2 * wl + 1) * 64, layer, h, lane, r1, Up, o[1], qf[1]); }
	ds_write_b128 v151, v[4:7] offset:4608
	v_pk_add_f32 v[4:5], v[12:13], 1.0 op_sel_hi:[1,0] neg_lo:[1,0] neg_hi:[1,0]
	v_pk_add_f32 v[6:7], v[14:15], 1.0 op_sel_hi:[1,0] neg_lo:[1,0] neg_hi:[1,0]
	v_pk_add_f32 v[8:9], v[16:17], 1.0 op_sel_hi:[1,0] neg_lo:[1,0] neg_hi:[1,0]
	v_pk_add_f32 v[10:11], v[18:19], 1.0 op_sel_hi:[1,0] neg_lo:[1,0] neg_hi:[1,0]
	v_pk_mul_f32 v[4:5], v[2:3], v[4:5] op_sel_hi:[0,1]
	v_pk_mul_f32 v[6:7], v[2:3], v[6:7] op_sel_hi:[0,1]
	v_pk_mul_f32 v[8:9], v[2:3], v[8:9] op_sel_hi:[0,1]
	v_pk_mul_f32 v[2:3], v[2:3], v[10:11] op_sel_hi:[0,1]
	v_pk_mul_f32 v[6:7], v[6:7], v[28:29]
	v_pk_mul_f32 v[2:3], v[2:3], v[32:33]
	v_pk_mul_f32 v[4:5], v[4:5], v[26:27]
	v_pk_mul_f32 v[8:9], v[8:9], v[30:31]
	v_bfe_u32 v1, v7, 16, 1
	v_bfe_u32 v10, v6, 16, 1
	v_bfe_u32 v11, v3, 16, 1
	v_bfe_u32 v12, v2, 16, 1
	v_add3_u32 v6, v6, v10, s73
	v_add3_u32 v1, v7, v1, s73
	v_add3_u32 v7, v2, v12, s73
	v_add3_u32 v10, v3, v11, s73
	v_bfe_u32 v2, v8, 16, 1
	v_bfe_u32 v3, v9, 16, 1
	v_bfe_u32 v11, v4, 16, 1
	v_bfe_u32 v12, v5, 16, 1
	v_add3_u32 v5, v5, v12, s73
	v_add3_u32 v4, v4, v11, s73
	v_add3_u32 v3, v9, v3, s73
	v_add3_u32 v2, v8, v2, s73
	v_lshrrev_b32_e32 v8, 16, v2
	v_lshrrev_b32_e32 v9, 16, v3
	v_lshrrev_b32_e32 v2, 16, v4
	v_lshrrev_b32_e32 v3, 16, v5
	v_and_or_b32 v3, v1, s26, v3
	v_and_or_b32 v2, v6, s26, v2
	v_and_or_b32 v5, v10, s26, v9
	v_and_or_b32 v4, v7, s26, v8
	ds_write_b128 v151, v[2:5] offset:4624
	s_waitcnt lgkmcnt(0)
	v_mov_b32_e32 v1, 0
	v_mov_b32_e32 v2, 0
	v_mov_b32_e32 v3, 0
	s_and_saveexec_b64 s[2:3], s[40:41]
	ds_read_b128 v[0:3], v152 offset:7680
	s_or_b64 exec, exec, s[2:3]
	v_mov_b32_e32 v4, 0
	v_mov_b32_e32 v8, 0
	v_mov_b32_e32 v9, 0
	v_mov_b32_e32 v10, 0
	v_mov_b32_e32 v11, 0
	s_and_saveexec_b64 s[2:3], s[40:41]
	ds_read_b128 v[8:11], v152 offset:8448
	s_or_b64 exec, exec, s[2:3]
	v_mov_b32_e32 v5, 0
	v_mov_b32_e32 v6, 0
	v_mov_b32_e32 v7, 0
	s_and_saveexec_b64 s[2:3], s[40:41]
	ds_read_b128 v[4:7], v152 offset:9216
	s_or_b64 exec, exec, s[2:3]
	v_mov_b32_e32 v12, 0
	v_mov_b32_e32 v64, 0
	v_mov_b32_e32 v65, 0
	v_mov_b32_e32 v66, 0
	v_mov_b32_e32 v67, 0
	s_and_saveexec_b64 s[2:3], s[40:41]
	ds_read_b128 v[64:67], v152 offset:9984
	s_or_b64 exec, exec, s[2:3]
	v_mov_b32_e32 v13, 0
	v_mov_b32_e32 v14, 0
	v_mov_b32_e32 v15, 0
	s_and_saveexec_b64 s[2:3], s[40:41]
	ds_read_b128 v[12:15], v152 offset:4608
	s_or_b64 exec, exec, s[2:3]
	s_waitcnt lgkmcnt(0)
	v_mfma_f32_16x16x32_bf16 v[60:63], v[12:15], v[0:3], 0
	v_mov_b32_e32 v16, 0
	v_mov_b32_e32 v17, 0
	v_mfma_f32_16x16x32_bf16 v[56:59], v[12:15], v[8:11], 0
	v_mfma_f32_16x16x32_bf16 v[52:55], v[12:15], v[4:7], 0
	v_mfma_f32_16x16x32_bf16 v[48:51], v[12:15], v[64:67], 0
	v_mov_b32_e32 v12, 0
	v_mov_b32_e32 v14, 0
	v_mov_b32_e32 v15, 0
	s_and_saveexec_b64 s[2:3], s[40:41]
	ds_read_b128 v[14:17], v152 offset:5376
	s_or_b64 exec, exec, s[2:3]
	s_waitcnt lgkmcnt(0)
	v_mfma_f32_16x16x32_bf16 v[44:47], v[14:17], v[0:3], 0
	v_mov_b32_e32 v13, 0
	v_mfma_f32_16x16x32_bf16 v[40:43], v[14:17], v[8:11], 0
	v_mfma_f32_16x16x32_bf16 v[36:39], v[14:17], v[4:7], 0
	v_mfma_f32_16x16x32_bf16 v[32:35], v[14:17], v[64:67], 0
	v_mov_b32_e32 v14, 0
	v_mov_b32_e32 v15, 0
	s_and_saveexec_b64 s[2:3], s[40:41]
	ds_read_b128 v[12:15], v152 offset:6144
	s_or_b64 exec, exec, s[2:3]
	s_waitcnt lgkmcnt(0)
	v_mfma_f32_16x16x32_bf16 v[28:31], v[12:15], v[0:3], 0
	v_mov_b32_e32 v80, 0
	v_mov_b32_e32 v68, 0
	v_mov_b32_e32 v69, 0
	v_mfma_f32_16x16x32_bf16 v[24:27], v[12:15], v[8:11], 0
	v_mov_b32_e32 v70, 0
	v_mov_b32_e32 v71, 0
	v_mfma_f32_16x16x32_bf16 v[20:23], v[12:15], v[4:7], 0
	v_mfma_f32_16x16x32_bf16 v[16:19], v[12:15], v[64:67], 0
	s_and_saveexec_b64 s[2:3], s[40:41]
	ds_read_b128 v[68:71], v152 offset:6912
	s_or_b64 exec, exec, s[2:3]
	s_waitcnt lgkmcnt(0)
	v_mfma_f32_16x16x32_bf16 v[12:15], v[68:71], v[0:3], 0
	v_mfma_f32_16x16x32_bf16 v[8:11], v[68:71], v[8:11], 0
	v_mfma_f32_16x16x32_bf16 v[4:7], v[68:71], v[4:7], 0
	v_mfma_f32_16x16x32_bf16 v[0:3], v[68:71], v[64:67], 0
	v_mov_b32_e32 v144, v140
	s_or_b64 s[2:3], s[24:25], s[12:13]
	v_ashrrev_i32_e32 v82, 3, v144
	v_ashrrev_i32_e32 v83, 31, v82
	v_lshl_add_u64 v[64:65], s[2:3], 0, v[82:83]
	v_mov_b64_e32 v[66:67], s[60:61]
	v_mad_u64_u32 v[66:67], s[2:3], v64, s93, v[66:67]
	v_mov_b32_e32 v64, v67
	v_mad_u64_u32 v[64:65], s[2:3], v65, s93, v[64:65]
	v_mov_b32_e32 v67, v64
	v_lshl_add_u64 v[64:65], v[66:67], 0, s[62:63]
	v_lshlrev_b32_e32 v66, 4, v144
	v_and_b32_e32 v84, 0x70, v66
	v_mov_b32_e32 v85, v221
	v_lshl_add_u64 v[72:73], v[64:65], 0, v[84:85]
	v_add_co_u32_e32 v76, vcc, s55, v72
	v_addc_co_u32_e32 v77, vcc, 0, v73, vcc
	s_movk_i32 s2, 0x90
	v_mul_lo_u32 v81, v82, s2
	v_add3_u32 v81, s9, v84, v81
	s_waitcnt lgkmcnt(0)
	s_and_b64 vcc, exec, s[0:1]
	s_waitcnt vmcnt(0)
	ds_write_b128 v81, v[160:163]
	ds_write_b128 v81, v[164:167] offset:2304
	ds_write_b128 v81, v[168:171] offset:1152
	ds_write_b128 v81, v[172:175] offset:3456
	s_waitcnt lgkmcnt(0)
	s_cbranch_vccnz .LBB0_480
	v_mov_b32_e32 v80, v177
